# P3 layer 0 too: quarter-full third round split by rows over all 256 WGs
# baseline (speedup 1.0000x reference)
.Lp3_skew1:
	s_nop 7
	s_nop 1
	s_cmp_lt_u32 s20, 0x80
	v_readlane_b32 s4, v254, 55
	v_readlane_b32 s5, v254, 56
	v_readlane_b32 s2, v254, 12
	v_readlane_b32 s3, v254, 13
	s_cselect_b32 s46, s2, s4
	s_cselect_b32 s47, s3, s5
	s_cselect_b32 s42, s12, s10
	s_cselect_b32 s43, s13, s11
	s_and_b32 s2, s20, 0x7f
	s_lshl_b32 s2, s2, 20
	s_lshl_b32 s3, s19, 10
	s_add_i32 s2, s2, s3
	s_add_u32 s42, s42, s2
	s_addc_u32 s43, s43, 0
	s_add_u32 s46, s46, s2
	s_addc_u32 s47, s47, 0
	s_lshr_b32 s2, s20, 3
	s_cmp_lt_u32 s20, 0x80
	s_cselect_b32 s2, s2, 16
	s_add_i32 s2, s2, s54
	s_mul_i32 s2, s2, 0x6000
	s_add_i32 s2, s2, s3
	s_add_i32 s2, s2, 0x2000
	v_readlane_b32 s4, v254, 14
	v_readlane_b32 s5, v254, 15
	s_nop 3
	s_add_u32 s44, s4, s2
	s_addc_u32 s45, s5, 0
	v_and_b32_e32 v197, 15, v222
	v_lshrrev_b32_e32 v198, 8, v222
	v_lshl_or_b32 v197, v198, 7, v197
	v_bfe_u32 v198, v222, 6, 2
	v_bfe_u32 v199, v222, 4, 2
	v_lshlrev_b32_e32 v199, 4, v199
	v_lshl_or_b32 v196, v198, 8, v199
	v_lshl_or_b32 v194, v197, 12, v196
	v_mov_b32_e32 v195, v194
	global_load_dwordx4 v[178:181], v196, s[44:45] offset:0
	global_load_dwordx4 v[182:185], v196, s[44:45] offset:64
	global_load_dwordx4 v[186:189], v196, s[44:45] offset:128
	global_load_dwordx4 v[190:193], v196, s[44:45] offset:192
	global_load_dwordx4 v[130:133], v194, s[42:43] offset:0
	global_load_dwordx4 v[134:137], v194, s[42:43] offset:64
	global_load_dwordx4 v[138:141], v194, s[42:43] offset:128
	global_load_dwordx4 v[142:145], v194, s[42:43] offset:192
	v_add_u32_e32 v194, 0x10000, v194
	global_load_dwordx4 v[146:149], v194, s[42:43] offset:0
	global_load_dwordx4 v[150:153], v194, s[42:43] offset:64
	global_load_dwordx4 v[154:157], v194, s[42:43] offset:128
	global_load_dwordx4 v[158:161], v194, s[42:43] offset:192
	v_add_u32_e32 v194, 0x10000, v194
	global_load_dwordx4 v[162:165], v194, s[42:43] offset:0
	global_load_dwordx4 v[166:169], v194, s[42:43] offset:64
	global_load_dwordx4 v[170:173], v194, s[42:43] offset:128
	global_load_dwordx4 v[174:177], v194, s[42:43] offset:192
	v_add_u32_e32 v194, 0x10000, v194
	s_add_i32 s2, s29, s95
	s_cmp_lt_i32 s2, 0x200
	s_cselect_b32 s17, 1, 0
	s_cselect_b32 s29, s2, s29
	s_lshr_b32 s2, s29, 5
	s_lshl_b32 s2, s2, 3
	s_and_b32 s3, s29, 7
	s_add_i32 s20, s2, s3
	s_bfe_u32 s19, s29, 0x20003
	s_lshl_b32 s2, s20, 19
	s_add_u32 s36, s64, s2
	s_addc_u32 s37, s65, 0
	s_lshl_b32 s2, s19, 19
	s_add_u32 s38, s7, s2
	s_addc_u32 s39, s28, 0
	s_mov_b32 m0, s21
	s_nop 0
	global_load_lds_dwordx4 v1, s[36:37]
	s_add_i32 m0, s21, 0x2000
	s_add_u32 s40, s36, 0x20000
	s_addc_u32 s41, s37, 0
	global_load_lds_dwordx4 v1, s[40:41]
	s_add_i32 m0, s21, 0x4000
	s_add_u32 s40, s36, 0x40000
	s_addc_u32 s41, s37, 0
	global_load_lds_dwordx4 v1, s[40:41]
	s_add_i32 m0, s21, 0x6000
	s_add_u32 s40, s36, 0x60000
	s_addc_u32 s41, s37, 0
	global_load_lds_dwordx4 v1, s[40:41]
	s_add_i32 m0, s21, 0x8000
	s_nop 0
	global_load_lds_dwordx4 v1, s[38:39]
	s_add_i32 m0, s21, 0xa000
	s_add_u32 s40, s38, 0x20000
	s_addc_u32 s41, s39, 0
	global_load_lds_dwordx4 v1, s[40:41]
	s_add_i32 m0, s21, 0xc000
	s_add_u32 s40, s38, 0x40000
	s_addc_u32 s41, s39, 0
	global_load_lds_dwordx4 v1, s[40:41]
	s_add_i32 m0, s21, 0xe000
	s_add_u32 s40, s38, 0x60000
	s_addc_u32 s41, s39, 0
	global_load_lds_dwordx4 v1, s[40:41]
	s_waitcnt vmcnt(16)
	v_pk_fma_f32 v[126:127], v[126:127], v[178:179], v[130:131]
	v_pk_fma_f32 v[128:129], v[128:129], v[180:181], v[132:133]
	v_pk_fma_f32 v[122:123], v[122:123], v[182:183], v[134:135]
	v_pk_fma_f32 v[124:125], v[124:125], v[184:185], v[136:137]
	v_pk_fma_f32 v[118:119], v[118:119], v[186:187], v[138:139]
	v_pk_fma_f32 v[120:121], v[120:121], v[188:189], v[140:141]
	v_pk_fma_f32 v[114:115], v[114:115], v[190:191], v[142:143]
	v_pk_fma_f32 v[116:117], v[116:117], v[192:193], v[144:145]
	global_store_dwordx4 v195, v[126:129], s[46:47] offset:0
	global_store_dwordx4 v195, v[122:125], s[46:47] offset:64
	global_store_dwordx4 v195, v[118:121], s[46:47] offset:128
	global_store_dwordx4 v195, v[114:117], s[46:47] offset:192
	global_load_dwordx4 v[130:133], v194, s[42:43] offset:0
	global_load_dwordx4 v[134:137], v194, s[42:43] offset:64
	global_load_dwordx4 v[138:141], v194, s[42:43] offset:128
	global_load_dwordx4 v[142:145], v194, s[42:43] offset:192
	v_add_u32_e32 v194, 0x10000, v194
	s_waitcnt vmcnt(20)
	v_add_u32_e32 v195, 0x10000, v195
	v_pk_fma_f32 v[110:111], v[110:111], v[178:179], v[146:147]
	v_pk_fma_f32 v[112:113], v[112:113], v[180:181], v[148:149]
	v_pk_fma_f32 v[106:107], v[106:107], v[182:183], v[150:151]
	v_pk_fma_f32 v[108:109], v[108:109], v[184:185], v[152:153]
	v_pk_fma_f32 v[102:103], v[102:103], v[186:187], v[154:155]
	v_pk_fma_f32 v[104:105], v[104:105], v[188:189], v[156:157]
	v_pk_fma_f32 v[98:99], v[98:99], v[190:191], v[158:159]
	v_pk_fma_f32 v[100:101], v[100:101], v[192:193], v[160:161]
	global_store_dwordx4 v195, v[110:113], s[46:47] offset:0
	global_store_dwordx4 v195, v[106:109], s[46:47] offset:64
	global_store_dwordx4 v195, v[102:105], s[46:47] offset:128
	global_store_dwordx4 v195, v[98:101], s[46:47] offset:192
	global_load_dwordx4 v[146:149], v194, s[42:43] offset:0
	global_load_dwordx4 v[150:153], v194, s[42:43] offset:64
	global_load_dwordx4 v[154:157], v194, s[42:43] offset:128
	global_load_dwordx4 v[158:161], v194, s[42:43] offset:192
	v_add_u32_e32 v194, 0x10000, v194
	s_waitcnt vmcnt(24)
	v_add_u32_e32 v195, 0x10000, v195
	v_pk_fma_f32 v[94:95], v[94:95], v[178:179], v[162:163]
	v_pk_fma_f32 v[96:97], v[96:97], v[180:181], v[164:165]
	v_pk_fma_f32 v[90:91], v[90:91], v[182:183], v[166:167]
	v_pk_fma_f32 v[92:93], v[92:93], v[184:185], v[168:169]
	v_pk_fma_f32 v[86:87], v[86:87], v[186:187], v[170:171]
	v_pk_fma_f32 v[88:89], v[88:89], v[188:189], v[172:173]
	v_pk_fma_f32 v[82:83], v[82:83], v[190:191], v[174:175]
	v_pk_fma_f32 v[84:85], v[84:85], v[192:193], v[176:177]
	global_store_dwordx4 v195, v[94:97], s[46:47] offset:0
	global_store_dwordx4 v195, v[90:93], s[46:47] offset:64
	global_store_dwordx4 v195, v[86:89], s[46:47] offset:128
	global_store_dwordx4 v195, v[82:85], s[46:47] offset:192
	global_load_dwordx4 v[162:165], v194, s[42:43] offset:0
	global_load_dwordx4 v[166:169], v194, s[42:43] offset:64
	global_load_dwordx4 v[170:173], v194, s[42:43] offset:128
	global_load_dwordx4 v[174:177], v194, s[42:43] offset:192
	v_add_u32_e32 v194, 0x10000, v194
	s_waitcnt vmcnt(16)
	v_add_u32_e32 v195, 0x10000, v195
	v_pk_fma_f32 v[78:79], v[78:79], v[178:179], v[130:131]
	v_pk_fma_f32 v[80:81], v[80:81], v[180:181], v[132:133]
	v_pk_fma_f32 v[74:75], v[74:75], v[182:183], v[134:135]
	v_pk_fma_f32 v[76:77], v[76:77], v[184:185], v[136:137]
	v_pk_fma_f32 v[70:71], v[70:71], v[186:187], v[138:139]
	v_pk_fma_f32 v[72:73], v[72:73], v[188:189], v[140:141]
	v_pk_fma_f32 v[66:67], v[66:67], v[190:191], v[142:143]
	v_pk_fma_f32 v[68:69], v[68:69], v[192:193], v[144:145]
	global_store_dwordx4 v195, v[78:81], s[46:47] offset:0
	global_store_dwordx4 v195, v[74:77], s[46:47] offset:64
	global_store_dwordx4 v195, v[70:73], s[46:47] offset:128
	global_store_dwordx4 v195, v[66:69], s[46:47] offset:192
	global_load_dwordx4 v[130:133], v194, s[42:43] offset:0
	global_load_dwordx4 v[134:137], v194, s[42:43] offset:64
	global_load_dwordx4 v[138:141], v194, s[42:43] offset:128
	global_load_dwordx4 v[142:145], v194, s[42:43] offset:192
	v_add_u32_e32 v194, 0x10000, v194
	s_waitcnt vmcnt(16)
	v_add_u32_e32 v195, 0x10000, v195
	v_pk_fma_f32 v[62:63], v[62:63], v[178:179], v[146:147]
	v_pk_fma_f32 v[64:65], v[64:65], v[180:181], v[148:149]
	v_pk_fma_f32 v[58:59], v[58:59], v[182:183], v[150:151]
	v_pk_fma_f32 v[60:61], v[60:61], v[184:185], v[152:153]
	v_pk_fma_f32 v[54:55], v[54:55], v[186:187], v[154:155]
	v_pk_fma_f32 v[56:57], v[56:57], v[188:189], v[156:157]
	v_pk_fma_f32 v[50:51], v[50:51], v[190:191], v[158:159]
	v_pk_fma_f32 v[52:53], v[52:53], v[192:193], v[160:161]
	global_store_dwordx4 v195, v[62:65], s[46:47] offset:0
	global_store_dwordx4 v195, v[58:61], s[46:47] offset:64
	global_store_dwordx4 v195, v[54:57], s[46:47] offset:128
	global_store_dwordx4 v195, v[50:53], s[46:47] offset:192
	global_load_dwordx4 v[146:149], v194, s[42:43] offset:0
	global_load_dwordx4 v[150:153], v194, s[42:43] offset:64
	global_load_dwordx4 v[154:157], v194, s[42:43] offset:128
	global_load_dwordx4 v[158:161], v194, s[42:43] offset:192
	v_add_u32_e32 v194, 0x10000, v194
	s_waitcnt vmcnt(16)
	v_add_u32_e32 v195, 0x10000, v195
	v_pk_fma_f32 v[46:47], v[46:47], v[178:179], v[162:163]
	v_pk_fma_f32 v[48:49], v[48:49], v[180:181], v[164:165]
	v_pk_fma_f32 v[42:43], v[42:43], v[182:183], v[166:167]
	v_pk_fma_f32 v[44:45], v[44:45], v[184:185], v[168:169]
	v_pk_fma_f32 v[38:39], v[38:39], v[186:187], v[170:171]
	v_pk_fma_f32 v[40:41], v[40:41], v[188:189], v[172:173]
	v_pk_fma_f32 v[34:35], v[34:35], v[190:191], v[174:175]
	v_pk_fma_f32 v[36:37], v[36:37], v[192:193], v[176:177]
	global_store_dwordx4 v195, v[46:49], s[46:47] offset:0
	global_store_dwordx4 v195, v[42:45], s[46:47] offset:64
	global_store_dwordx4 v195, v[38:41], s[46:47] offset:128
	global_store_dwordx4 v195, v[34:37], s[46:47] offset:192
	s_waitcnt vmcnt(12)
	v_add_u32_e32 v195, 0x10000, v195
	v_pk_fma_f32 v[30:31], v[30:31], v[178:179], v[130:131]
	v_pk_fma_f32 v[32:33], v[32:33], v[180:181], v[132:133]
	v_pk_fma_f32 v[26:27], v[26:27], v[182:183], v[134:135]
	v_pk_fma_f32 v[28:29], v[28:29], v[184:185], v[136:137]
	v_pk_fma_f32 v[22:23], v[22:23], v[186:187], v[138:139]
	v_pk_fma_f32 v[24:25], v[24:25], v[188:189], v[140:141]
	v_pk_fma_f32 v[18:19], v[18:19], v[190:191], v[142:143]
	v_pk_fma_f32 v[20:21], v[20:21], v[192:193], v[144:145]
	global_store_dwordx4 v195, v[30:33], s[46:47] offset:0
	global_store_dwordx4 v195, v[26:29], s[46:47] offset:64
	global_store_dwordx4 v195, v[22:25], s[46:47] offset:128
	global_store_dwordx4 v195, v[18:21], s[46:47] offset:192
	s_waitcnt vmcnt(8)
	v_add_u32_e32 v195, 0x10000, v195
	v_pk_fma_f32 v[14:15], v[14:15], v[178:179], v[146:147]
	v_pk_fma_f32 v[16:17], v[16:17], v[180:181], v[148:149]
	v_pk_fma_f32 v[10:11], v[10:11], v[182:183], v[150:151]
	v_pk_fma_f32 v[12:13], v[12:13], v[184:185], v[152:153]
	v_pk_fma_f32 v[6:7], v[6:7], v[186:187], v[154:155]
	v_pk_fma_f32 v[8:9], v[8:9], v[188:189], v[156:157]
	v_pk_fma_f32 v[2:3], v[2:3], v[190:191], v[158:159]
	v_pk_fma_f32 v[4:5], v[4:5], v[192:193], v[160:161]
	global_store_dwordx4 v195, v[14:17], s[46:47] offset:0
	global_store_dwordx4 v195, v[10:13], s[46:47] offset:64
	global_store_dwordx4 v195, v[6:9], s[46:47] offset:128
	global_store_dwordx4 v195, v[2:5], s[46:47] offset:192
	s_cmp_lg_u32 s17, 0
	s_cbranch_scc1 .Lp3_cont
	s_cmp_lg_u32 s54, 0
	s_cbranch_scc1 .Lp3t_none
	s_waitcnt vmcnt(0)
	v_readlane_b32 s2, v255, 22
	s_nop 0
	s_and_b32 s4, s2, 3
	s_lshr_b32 s2, s2, 2
	s_add_i32 s29, s2, 0x200
	s_lshr_b32 s2, s29, 5
	s_lshl_b32 s2, s2, 3
	s_and_b32 s3, s29, 7
	s_add_i32 s20, s2, s3
	s_bfe_u32 s19, s29, 0x20003
	s_lshl_b32 s2, s20, 19
	s_add_u32 s36, s64, s2
	s_addc_u32 s37, s65, 0
	s_lshl_b32 s2, s19, 19
	s_add_u32 s38, s7, s2
	s_addc_u32 s39, s28, 0
	s_mul_i32 s2, s4, 0x20000
	s_add_u32 s36, s36, s2
	s_addc_u32 s37, s37, 0
	s_lshl_b32 s17, s4, 18
	v_and_b32_e32 v194, 15, v222
	v_bfe_u32 v195, v222, 4, 2
	v_bfe_u32 v196, v194, 1, 3
	v_xor_b32_e32 v195, v195, v196
	v_lshlrev_b32_e32 v195, 4, v195
	v_lshrrev_b32_e32 v196, 8, v222
	v_lshl_or_b32 v196, v196, 5, v194
	v_lshl_or_b32 v200, v196, 7, v195
	v_xor_b32_e32 v201, 64, v200
	v_bfe_u32 v196, v222, 6, 2
	v_lshl_or_b32 v196, v196, 6, v194
	v_lshl_or_b32 v202, v196, 7, v195
	v_xor_b32_e32 v203, 64, v202
	v_add_u32_e32 v204, 0x10000, v200
	v_add_u32_e32 v205, 0x10000, v201
	v_add_u32_e32 v206, 0x10000, v202
	v_add_u32_e32 v207, 0x10000, v203
	v_readfirstlane_b32 s21, v222
	s_nop 3
	s_lshr_b32 s22, s21, 8
	s_lshr_b32 s21, s21, 6
	s_lshl_b32 s21, s21, 10
	s_barrier
	s_mov_b32 m0, s21
	s_nop 0
	global_load_lds_dwordx4 v1, s[36:37]
	s_add_i32 m0, s21, 0x2000
	s_nop 0
	global_load_lds_dwordx4 v1, s[36:37]
	s_add_i32 m0, s21, 0x4000
	s_nop 0
	global_load_lds_dwordx4 v1, s[36:37]
	s_add_i32 m0, s21, 0x6000
	s_nop 0
	global_load_lds_dwordx4 v1, s[36:37]
	s_add_i32 m0, s21, 0x8000
	s_nop 0
	global_load_lds_dwordx4 v1, s[38:39]
	s_add_i32 m0, s21, 0xa000
	s_add_u32 s40, s38, 0x20000
	s_addc_u32 s41, s39, 0
	global_load_lds_dwordx4 v1, s[40:41]
	s_add_i32 m0, s21, 0xc000
	s_add_u32 s40, s38, 0x40000
	s_addc_u32 s41, s39, 0
	global_load_lds_dwordx4 v1, s[40:41]
	s_add_i32 m0, s21, 0xe000
	s_add_u32 s40, s38, 0x60000
	s_addc_u32 s41, s39, 0
	global_load_lds_dwordx4 v1, s[40:41]
	s_add_i32 m0, s21, 0x10000
	s_add_u32 s40, s36, 0x80
	s_addc_u32 s41, s37, 0
	global_load_lds_dwordx4 v1, s[40:41]
	s_add_i32 m0, s21, 0x18000
	s_add_u32 s40, s38, 0x80
	s_addc_u32 s41, s39, 0
	global_load_lds_dwordx4 v1, s[40:41]
	s_waitcnt vmcnt(2)
	s_barrier
	s_cmp_eq_u32 s22, 0
	s_cbranch_scc1 .Lp3t_skew0
	s_barrier
.Lp3t_skew0:
	ds_read_b128 v[130:133], v200 offset:0
	ds_read_b128 v[134:137], v200 offset:2048
	ds_read_b128 v[162:165], v202 offset:32768
	ds_read_b128 v[166:169], v202 offset:34816
	ds_read_b128 v[170:173], v202 offset:36864
	ds_read_b128 v[174:177], v202 offset:38912
	s_add_i32 m0, s21, 0x14000
	s_add_u32 s40, s36, 0x80
	s_addc_u32 s41, s37, 0
	global_load_lds_dwordx4 v1, s[40:41]
	s_add_i32 m0, s21, 0x1a000
	s_add_u32 s40, s38, 0x20080
	s_addc_u32 s41, s39, 0
	global_load_lds_dwordx4 v1, s[40:41]
	s_waitcnt lgkmcnt(0)
	s_barrier
	v_mfma_f32_16x16x32_f16 v[126:129], v[162:165], v[130:133], 0
	v_mfma_f32_16x16x32_f16 v[122:125], v[166:169], v[130:133], 0
	v_mfma_f32_16x16x32_f16 v[118:121], v[170:173], v[130:133], 0
	v_mfma_f32_16x16x32_f16 v[114:117], v[174:177], v[130:133], 0
	v_mfma_f32_16x16x32_f16 v[110:113], v[162:165], v[134:137], 0
	v_mfma_f32_16x16x32_f16 v[106:109], v[166:169], v[134:137], 0
	v_mfma_f32_16x16x32_f16 v[102:105], v[170:173], v[134:137], 0
	v_mfma_f32_16x16x32_f16 v[98:101], v[174:177], v[134:137], 0
	s_barrier
	s_add_i32 m0, s21, 0x1c000
	s_add_u32 s40, s38, 0x40080
	s_addc_u32 s41, s39, 0
	global_load_lds_dwordx4 v1, s[40:41]
	s_add_i32 m0, s21, 0x1e000
	s_add_u32 s40, s38, 0x60080
	s_addc_u32 s41, s39, 0
	global_load_lds_dwordx4 v1, s[40:41]
	s_waitcnt lgkmcnt(0)
	s_barrier
	s_barrier
	ds_read_b128 v[130:133], v201 offset:0
	ds_read_b128 v[134:137], v201 offset:2048
	ds_read_b128 v[162:165], v203 offset:32768
	ds_read_b128 v[166:169], v203 offset:34816
	ds_read_b128 v[170:173], v203 offset:36864
	ds_read_b128 v[174:177], v203 offset:38912
	s_add_i32 m0, s21, 0x12000
	s_add_u32 s40, s36, 0x80
	s_addc_u32 s41, s37, 0
	global_load_lds_dwordx4 v1, s[40:41]
	s_add_i32 m0, s21, 0x16000
	s_add_u32 s40, s36, 0x80
	s_addc_u32 s41, s37, 0
	global_load_lds_dwordx4 v1, s[40:41]
	s_waitcnt lgkmcnt(0)
	s_barrier
	v_mfma_f32_16x16x32_f16 v[126:129], v[162:165], v[130:133], v[126:129]
	v_mfma_f32_16x16x32_f16 v[122:125], v[166:169], v[130:133], v[122:125]
	v_mfma_f32_16x16x32_f16 v[118:121], v[170:173], v[130:133], v[118:121]
	v_mfma_f32_16x16x32_f16 v[114:117], v[174:177], v[130:133], v[114:117]
	v_mfma_f32_16x16x32_f16 v[110:113], v[162:165], v[134:137], v[110:113]
	v_mfma_f32_16x16x32_f16 v[106:109], v[166:169], v[134:137], v[106:109]
	v_mfma_f32_16x16x32_f16 v[102:105], v[170:173], v[134:137], v[102:105]
	v_mfma_f32_16x16x32_f16 v[98:101], v[174:177], v[134:137], v[98:101]
	s_barrier
	s_mov_b32 m0, s21
	s_add_u32 s40, s36, 0x100
	s_addc_u32 s41, s37, 0
	global_load_lds_dwordx4 v1, s[40:41]
	s_add_i32 m0, s21, 0x8000
	s_add_u32 s40, s38, 0x100
	s_addc_u32 s41, s39, 0
	global_load_lds_dwordx4 v1, s[40:41]
	s_waitcnt vmcnt(4) lgkmcnt(0)
	s_barrier
	s_barrier
	s_add_u32 s36, s36, 0x80
	s_addc_u32 s37, s37, 0
	s_add_u32 s38, s38, 0x80
	s_addc_u32 s39, s39, 0
	ds_read_b128 v[130:133], v204 offset:0
	ds_read_b128 v[134:137], v204 offset:2048
	ds_read_b128 v[162:165], v206 offset:32768
	ds_read_b128 v[166:169], v206 offset:34816
	ds_read_b128 v[170:173], v206 offset:36864
	ds_read_b128 v[174:177], v206 offset:38912
	s_add_i32 m0, s21, 0x4000
	s_add_u32 s40, s36, 0x80
	s_addc_u32 s41, s37, 0
	global_load_lds_dwordx4 v1, s[40:41]
	s_add_i32 m0, s21, 0xa000
	s_add_u32 s40, s38, 0x20080
	s_addc_u32 s41, s39, 0
	global_load_lds_dwordx4 v1, s[40:41]
	s_waitcnt vmcnt(4) lgkmcnt(0)
	s_barrier
	v_mfma_f32_16x16x32_f16 v[126:129], v[162:165], v[130:133], v[126:129]
	v_mfma_f32_16x16x32_f16 v[122:125], v[166:169], v[130:133], v[122:125]
	v_mfma_f32_16x16x32_f16 v[118:121], v[170:173], v[130:133], v[118:121]
	v_mfma_f32_16x16x32_f16 v[114:117], v[174:177], v[130:133], v[114:117]
	v_mfma_f32_16x16x32_f16 v[110:113], v[162:165], v[134:137], v[110:113]
	v_mfma_f32_16x16x32_f16 v[106:109], v[166:169], v[134:137], v[106:109]
	v_mfma_f32_16x16x32_f16 v[102:105], v[170:173], v[134:137], v[102:105]
	v_mfma_f32_16x16x32_f16 v[98:101], v[174:177], v[134:137], v[98:101]
	s_barrier
	s_add_i32 m0, s21, 0xc000
	s_add_u32 s40, s38, 0x40080
	s_addc_u32 s41, s39, 0
	global_load_lds_dwordx4 v1, s[40:41]
	s_add_i32 m0, s21, 0xe000
	s_add_u32 s40, s38, 0x60080
	s_addc_u32 s41, s39, 0
	global_load_lds_dwordx4 v1, s[40:41]
	s_waitcnt lgkmcnt(0)
	s_barrier
	s_barrier
	ds_read_b128 v[130:133], v205 offset:0
	ds_read_b128 v[134:137], v205 offset:2048
	ds_read_b128 v[162:165], v207 offset:32768
	ds_read_b128 v[166:169], v207 offset:34816
	ds_read_b128 v[170:173], v207 offset:36864
	ds_read_b128 v[174:177], v207 offset:38912
	s_add_i32 m0, s21, 0x2000
	s_add_u32 s40, s36, 0x80
	s_addc_u32 s41, s37, 0
	global_load_lds_dwordx4 v1, s[40:41]
	s_add_i32 m0, s21, 0x6000
	s_add_u32 s40, s36, 0x80
	s_addc_u32 s41, s37, 0
	global_load_lds_dwordx4 v1, s[40:41]
	s_waitcnt lgkmcnt(0)
	s_barrier
	v_mfma_f32_16x16x32_f16 v[126:129], v[162:165], v[130:133], v[126:129]
	v_mfma_f32_16x16x32_f16 v[122:125], v[166:169], v[130:133], v[122:125]
	v_mfma_f32_16x16x32_f16 v[118:121], v[170:173], v[130:133], v[118:121]
	v_mfma_f32_16x16x32_f16 v[114:117], v[174:177], v[130:133], v[114:117]
	v_mfma_f32_16x16x32_f16 v[110:113], v[162:165], v[134:137], v[110:113]
	v_mfma_f32_16x16x32_f16 v[106:109], v[166:169], v[134:137], v[106:109]
	v_mfma_f32_16x16x32_f16 v[102:105], v[170:173], v[134:137], v[102:105]
	v_mfma_f32_16x16x32_f16 v[98:101], v[174:177], v[134:137], v[98:101]
	s_barrier
	s_add_i32 m0, s21, 0x10000
	s_add_u32 s40, s36, 0x100
	s_addc_u32 s41, s37, 0
	global_load_lds_dwordx4 v1, s[40:41]
	s_add_i32 m0, s21, 0x18000
	s_add_u32 s40, s38, 0x100
	s_addc_u32 s41, s39, 0
	global_load_lds_dwordx4 v1, s[40:41]
	s_waitcnt vmcnt(4) lgkmcnt(0)
	s_barrier
	s_barrier
	s_add_u32 s36, s36, 0x80
	s_addc_u32 s37, s37, 0
	s_add_u32 s38, s38, 0x80
	s_addc_u32 s39, s39, 0
	s_movk_i32 s23, 6
.Lp3t_loop:
	ds_read_b128 v[130:133], v200 offset:0
	ds_read_b128 v[134:137], v200 offset:2048
	ds_read_b128 v[162:165], v202 offset:32768
	ds_read_b128 v[166:169], v202 offset:34816
	ds_read_b128 v[170:173], v202 offset:36864
	ds_read_b128 v[174:177], v202 offset:38912
	s_add_i32 m0, s21, 0x14000
	s_add_u32 s40, s36, 0x80
	s_addc_u32 s41, s37, 0
	global_load_lds_dwordx4 v1, s[40:41]
	s_add_i32 m0, s21, 0x1a000
	s_add_u32 s40, s38, 0x20080
	s_addc_u32 s41, s39, 0
	global_load_lds_dwordx4 v1, s[40:41]
	s_waitcnt vmcnt(4) lgkmcnt(0)
	s_barrier
	v_mfma_f32_16x16x32_f16 v[126:129], v[162:165], v[130:133], v[126:129]
	v_mfma_f32_16x16x32_f16 v[122:125], v[166:169], v[130:133], v[122:125]
	v_mfma_f32_16x16x32_f16 v[118:121], v[170:173], v[130:133], v[118:121]
	v_mfma_f32_16x16x32_f16 v[114:117], v[174:177], v[130:133], v[114:117]
	v_mfma_f32_16x16x32_f16 v[110:113], v[162:165], v[134:137], v[110:113]
	v_mfma_f32_16x16x32_f16 v[106:109], v[166:169], v[134:137], v[106:109]
	v_mfma_f32_16x16x32_f16 v[102:105], v[170:173], v[134:137], v[102:105]
	v_mfma_f32_16x16x32_f16 v[98:101], v[174:177], v[134:137], v[98:101]
	s_barrier
	s_add_i32 m0, s21, 0x1c000
	s_add_u32 s40, s38, 0x40080
	s_addc_u32 s41, s39, 0
	global_load_lds_dwordx4 v1, s[40:41]
	s_add_i32 m0, s21, 0x1e000
	s_add_u32 s40, s38, 0x60080
	s_addc_u32 s41, s39, 0
	global_load_lds_dwordx4 v1, s[40:41]
	s_waitcnt lgkmcnt(0)
	s_barrier
	s_barrier
	ds_read_b128 v[130:133], v201 offset:0
	ds_read_b128 v[134:137], v201 offset:2048
	ds_read_b128 v[162:165], v203 offset:32768
	ds_read_b128 v[166:169], v203 offset:34816
	ds_read_b128 v[170:173], v203 offset:36864
	ds_read_b128 v[174:177], v203 offset:38912
	s_add_i32 m0, s21, 0x12000
	s_add_u32 s40, s36, 0x80
	s_addc_u32 s41, s37, 0
	global_load_lds_dwordx4 v1, s[40:41]
	s_add_i32 m0, s21, 0x16000
	s_add_u32 s40, s36, 0x80
	s_addc_u32 s41, s37, 0
	global_load_lds_dwordx4 v1, s[40:41]
	s_waitcnt lgkmcnt(0)
	s_barrier
	v_mfma_f32_16x16x32_f16 v[126:129], v[162:165], v[130:133], v[126:129]
	v_mfma_f32_16x16x32_f16 v[122:125], v[166:169], v[130:133], v[122:125]
	v_mfma_f32_16x16x32_f16 v[118:121], v[170:173], v[130:133], v[118:121]
	v_mfma_f32_16x16x32_f16 v[114:117], v[174:177], v[130:133], v[114:117]
	v_mfma_f32_16x16x32_f16 v[110:113], v[162:165], v[134:137], v[110:113]
	v_mfma_f32_16x16x32_f16 v[106:109], v[166:169], v[134:137], v[106:109]
	v_mfma_f32_16x16x32_f16 v[102:105], v[170:173], v[134:137], v[102:105]
	v_mfma_f32_16x16x32_f16 v[98:101], v[174:177], v[134:137], v[98:101]
	s_barrier
	s_mov_b32 m0, s21
	s_add_u32 s40, s36, 0x100
	s_addc_u32 s41, s37, 0
	global_load_lds_dwordx4 v1, s[40:41]
	s_add_i32 m0, s21, 0x8000
	s_add_u32 s40, s38, 0x100
	s_addc_u32 s41, s39, 0
	global_load_lds_dwordx4 v1, s[40:41]
	s_waitcnt vmcnt(4) lgkmcnt(0)
	s_barrier
	s_barrier
	s_add_u32 s36, s36, 0x80
	s_addc_u32 s37, s37, 0
	s_add_u32 s38, s38, 0x80
	s_addc_u32 s39, s39, 0
	ds_read_b128 v[130:133], v204 offset:0
	ds_read_b128 v[134:137], v204 offset:2048
	ds_read_b128 v[162:165], v206 offset:32768
	ds_read_b128 v[166:169], v206 offset:34816
	ds_read_b128 v[170:173], v206 offset:36864
	ds_read_b128 v[174:177], v206 offset:38912
	s_add_i32 m0, s21, 0x4000
	s_add_u32 s40, s36, 0x80
	s_addc_u32 s41, s37, 0
	global_load_lds_dwordx4 v1, s[40:41]
	s_add_i32 m0, s21, 0xa000
	s_add_u32 s40, s38, 0x20080
	s_addc_u32 s41, s39, 0
	global_load_lds_dwordx4 v1, s[40:41]
	s_waitcnt vmcnt(4) lgkmcnt(0)
	s_barrier
	v_mfma_f32_16x16x32_f16 v[126:129], v[162:165], v[130:133], v[126:129]
	v_mfma_f32_16x16x32_f16 v[122:125], v[166:169], v[130:133], v[122:125]
	v_mfma_f32_16x16x32_f16 v[118:121], v[170:173], v[130:133], v[118:121]
	v_mfma_f32_16x16x32_f16 v[114:117], v[174:177], v[130:133], v[114:117]
	v_mfma_f32_16x16x32_f16 v[110:113], v[162:165], v[134:137], v[110:113]
	v_mfma_f32_16x16x32_f16 v[106:109], v[166:169], v[134:137], v[106:109]
	v_mfma_f32_16x16x32_f16 v[102:105], v[170:173], v[134:137], v[102:105]
	v_mfma_f32_16x16x32_f16 v[98:101], v[174:177], v[134:137], v[98:101]
	s_barrier
	s_add_i32 m0, s21, 0xc000
	s_add_u32 s40, s38, 0x40080
	s_addc_u32 s41, s39, 0
	global_load_lds_dwordx4 v1, s[40:41]
	s_add_i32 m0, s21, 0xe000
	s_add_u32 s40, s38, 0x60080
	s_addc_u32 s41, s39, 0
	global_load_lds_dwordx4 v1, s[40:41]
	s_waitcnt lgkmcnt(0)
	s_barrier
	s_barrier
	ds_read_b128 v[130:133], v205 offset:0
	ds_read_b128 v[134:137], v205 offset:2048
	ds_read_b128 v[162:165], v207 offset:32768
	ds_read_b128 v[166:169], v207 offset:34816
	ds_read_b128 v[170:173], v207 offset:36864
	ds_read_b128 v[174:177], v207 offset:38912
	s_add_i32 m0, s21, 0x2000
	s_add_u32 s40, s36, 0x80
	s_addc_u32 s41, s37, 0
	global_load_lds_dwordx4 v1, s[40:41]
	s_add_i32 m0, s21, 0x6000
	s_add_u32 s40, s36, 0x80
	s_addc_u32 s41, s37, 0
	global_load_lds_dwordx4 v1, s[40:41]
	s_waitcnt lgkmcnt(0)
	s_barrier
	v_mfma_f32_16x16x32_f16 v[126:129], v[162:165], v[130:133], v[126:129]
	v_mfma_f32_16x16x32_f16 v[122:125], v[166:169], v[130:133], v[122:125]
	v_mfma_f32_16x16x32_f16 v[118:121], v[170:173], v[130:133], v[118:121]
	v_mfma_f32_16x16x32_f16 v[114:117], v[174:177], v[130:133], v[114:117]
	v_mfma_f32_16x16x32_f16 v[110:113], v[162:165], v[134:137], v[110:113]
	v_mfma_f32_16x16x32_f16 v[106:109], v[166:169], v[134:137], v[106:109]
	v_mfma_f32_16x16x32_f16 v[102:105], v[170:173], v[134:137], v[102:105]
	v_mfma_f32_16x16x32_f16 v[98:101], v[174:177], v[134:137], v[98:101]
	s_barrier
	s_add_i32 m0, s21, 0x10000
	s_add_u32 s40, s36, 0x100
	s_addc_u32 s41, s37, 0
	global_load_lds_dwordx4 v1, s[40:41]
	s_add_i32 m0, s21, 0x18000
	s_add_u32 s40, s38, 0x100
	s_addc_u32 s41, s39, 0
	global_load_lds_dwordx4 v1, s[40:41]
	s_waitcnt vmcnt(4) lgkmcnt(0)
	s_barrier
	s_barrier
	s_add_u32 s36, s36, 0x80
	s_addc_u32 s37, s37, 0
	s_add_u32 s38, s38, 0x80
	s_addc_u32 s39, s39, 0
	s_add_i32 s23, s23, -1
	s_cmp_lg_u32 s23, 0
	s_cbranch_scc1 .Lp3t_loop
	ds_read_b128 v[130:133], v200 offset:0
	ds_read_b128 v[134:137], v200 offset:2048
	ds_read_b128 v[162:165], v202 offset:32768
	ds_read_b128 v[166:169], v202 offset:34816
	ds_read_b128 v[170:173], v202 offset:36864
	ds_read_b128 v[174:177], v202 offset:38912
	s_add_i32 m0, s21, 0x14000
	s_add_u32 s40, s36, 0x80
	s_addc_u32 s41, s37, 0
	global_load_lds_dwordx4 v1, s[40:41]
	s_add_i32 m0, s21, 0x1a000
	s_add_u32 s40, s38, 0x20080
	s_addc_u32 s41, s39, 0
	global_load_lds_dwordx4 v1, s[40:41]
	s_waitcnt vmcnt(4) lgkmcnt(0)
	s_barrier
	v_mfma_f32_16x16x32_f16 v[126:129], v[162:165], v[130:133], v[126:129]
	v_mfma_f32_16x16x32_f16 v[122:125], v[166:169], v[130:133], v[122:125]
	v_mfma_f32_16x16x32_f16 v[118:121], v[170:173], v[130:133], v[118:121]
	v_mfma_f32_16x16x32_f16 v[114:117], v[174:177], v[130:133], v[114:117]
	v_mfma_f32_16x16x32_f16 v[110:113], v[162:165], v[134:137], v[110:113]
	v_mfma_f32_16x16x32_f16 v[106:109], v[166:169], v[134:137], v[106:109]
	v_mfma_f32_16x16x32_f16 v[102:105], v[170:173], v[134:137], v[102:105]
	v_mfma_f32_16x16x32_f16 v[98:101], v[174:177], v[134:137], v[98:101]
	s_barrier
	s_add_i32 m0, s21, 0x1c000
	s_add_u32 s40, s38, 0x40080
	s_addc_u32 s41, s39, 0
	global_load_lds_dwordx4 v1, s[40:41]
	s_add_i32 m0, s21, 0x1e000
	s_add_u32 s40, s38, 0x60080
	s_addc_u32 s41, s39, 0
	global_load_lds_dwordx4 v1, s[40:41]
	s_waitcnt lgkmcnt(0)
	s_barrier
	s_barrier
	ds_read_b128 v[130:133], v201 offset:0
	ds_read_b128 v[134:137], v201 offset:2048
	ds_read_b128 v[162:165], v203 offset:32768
	ds_read_b128 v[166:169], v203 offset:34816
	ds_read_b128 v[170:173], v203 offset:36864
	ds_read_b128 v[174:177], v203 offset:38912
	s_add_i32 m0, s21, 0x12000
	s_add_u32 s40, s36, 0x80
	s_addc_u32 s41, s37, 0
	global_load_lds_dwordx4 v1, s[40:41]
	s_add_i32 m0, s21, 0x16000
	s_add_u32 s40, s36, 0x80
	s_addc_u32 s41, s37, 0
	global_load_lds_dwordx4 v1, s[40:41]
	s_waitcnt lgkmcnt(0)
	s_barrier
	v_mfma_f32_16x16x32_f16 v[126:129], v[162:165], v[130:133], v[126:129]
	v_mfma_f32_16x16x32_f16 v[122:125], v[166:169], v[130:133], v[122:125]
	v_mfma_f32_16x16x32_f16 v[118:121], v[170:173], v[130:133], v[118:121]
	v_mfma_f32_16x16x32_f16 v[114:117], v[174:177], v[130:133], v[114:117]
	v_mfma_f32_16x16x32_f16 v[110:113], v[162:165], v[134:137], v[110:113]
	v_mfma_f32_16x16x32_f16 v[106:109], v[166:169], v[134:137], v[106:109]
	v_mfma_f32_16x16x32_f16 v[102:105], v[170:173], v[134:137], v[102:105]
	v_mfma_f32_16x16x32_f16 v[98:101], v[174:177], v[134:137], v[98:101]
	s_barrier
	s_waitcnt vmcnt(2) lgkmcnt(0)
	s_barrier
	s_barrier
	s_add_u32 s36, s36, 0x80
	s_addc_u32 s37, s37, 0
	s_add_u32 s38, s38, 0x80
	s_addc_u32 s39, s39, 0
	ds_read_b128 v[130:133], v204 offset:0
	ds_read_b128 v[134:137], v204 offset:2048
	ds_read_b128 v[162:165], v206 offset:32768
	ds_read_b128 v[166:169], v206 offset:34816
	ds_read_b128 v[170:173], v206 offset:36864
	ds_read_b128 v[174:177], v206 offset:38912
	s_waitcnt vmcnt(0) lgkmcnt(0)
	s_barrier
	v_mfma_f32_16x16x32_f16 v[126:129], v[162:165], v[130:133], v[126:129]
	v_mfma_f32_16x16x32_f16 v[122:125], v[166:169], v[130:133], v[122:125]
	v_mfma_f32_16x16x32_f16 v[118:121], v[170:173], v[130:133], v[118:121]
	v_mfma_f32_16x16x32_f16 v[114:117], v[174:177], v[130:133], v[114:117]
	v_mfma_f32_16x16x32_f16 v[110:113], v[162:165], v[134:137], v[110:113]
	v_mfma_f32_16x16x32_f16 v[106:109], v[166:169], v[134:137], v[106:109]
	v_mfma_f32_16x16x32_f16 v[102:105], v[170:173], v[134:137], v[102:105]
	v_mfma_f32_16x16x32_f16 v[98:101], v[174:177], v[134:137], v[98:101]
	s_barrier
	s_waitcnt lgkmcnt(0)
	s_barrier
	s_barrier
	ds_read_b128 v[130:133], v205 offset:0
	ds_read_b128 v[134:137], v205 offset:2048
	ds_read_b128 v[162:165], v207 offset:32768
	ds_read_b128 v[166:169], v207 offset:34816
	ds_read_b128 v[170:173], v207 offset:36864
	ds_read_b128 v[174:177], v207 offset:38912
	s_waitcnt lgkmcnt(0)
	s_barrier
	v_mfma_f32_16x16x32_f16 v[126:129], v[162:165], v[130:133], v[126:129]
	v_mfma_f32_16x16x32_f16 v[122:125], v[166:169], v[130:133], v[122:125]
	v_mfma_f32_16x16x32_f16 v[118:121], v[170:173], v[130:133], v[118:121]
	v_mfma_f32_16x16x32_f16 v[114:117], v[174:177], v[130:133], v[114:117]
	v_mfma_f32_16x16x32_f16 v[110:113], v[162:165], v[134:137], v[110:113]
	v_mfma_f32_16x16x32_f16 v[106:109], v[166:169], v[134:137], v[106:109]
	v_mfma_f32_16x16x32_f16 v[102:105], v[170:173], v[134:137], v[102:105]
	v_mfma_f32_16x16x32_f16 v[98:101], v[174:177], v[134:137], v[98:101]
	s_barrier
	s_waitcnt lgkmcnt(0)
	s_barrier
	s_barrier
	s_cmp_eq_u32 s22, 1
	s_cbranch_scc1 .Lp3t_skew1
	s_barrier
.Lp3t_skew1:
	s_nop 7
	s_nop 1
	s_cmp_lt_u32 s20, 0x80
	v_readlane_b32 s2, v254, 12
	v_readlane_b32 s3, v254, 13
	v_readlane_b32 s4, v254, 55
	v_readlane_b32 s5, v254, 56
	s_cselect_b32 s46, s2, s4
	s_cselect_b32 s47, s3, s5
	s_cselect_b32 s42, s12, s10
	s_cselect_b32 s43, s13, s11
	s_and_b32 s2, s20, 0x7f
	s_lshl_b32 s2, s2, 20
	s_lshl_b32 s3, s19, 10
	s_add_i32 s2, s2, s3
	s_add_i32 s2, s2, s17
	s_add_u32 s42, s42, s2
	s_addc_u32 s43, s43, 0
	s_add_u32 s46, s46, s2
	s_addc_u32 s47, s47, 0
	s_lshr_b32 s2, s20, 3
	s_cmp_lt_u32 s20, 0x80
	s_cselect_b32 s2, s2, 16
	s_add_i32 s2, s2, s54
	s_mul_i32 s2, s2, 0x6000
	s_add_i32 s2, s2, s3
	s_add_i32 s2, s2, 0x2000
	v_readlane_b32 s4, v254, 14
	v_readlane_b32 s5, v254, 15
	s_nop 3
	s_add_u32 s44, s4, s2
	s_addc_u32 s45, s5, 0
	v_and_b32_e32 v197, 15, v222
	v_lshrrev_b32_e32 v198, 8, v222
	v_lshl_or_b32 v197, v198, 5, v197
	v_bfe_u32 v198, v222, 6, 2
	v_bfe_u32 v199, v222, 4, 2
	v_lshlrev_b32_e32 v199, 4, v199
	v_lshl_or_b32 v196, v198, 8, v199
	v_lshl_or_b32 v194, v197, 12, v196
	s_nop 1
	global_load_dwordx4 v[178:181], v196, s[44:45] offset:0
	global_load_dwordx4 v[182:185], v196, s[44:45] offset:64
	global_load_dwordx4 v[186:189], v196, s[44:45] offset:128
	global_load_dwordx4 v[190:193], v196, s[44:45] offset:192
	global_load_dwordx4 v[130:133], v194, s[42:43] offset:0
	global_load_dwordx4 v[134:137], v194, s[42:43] offset:64
	global_load_dwordx4 v[138:141], v194, s[42:43] offset:128
	global_load_dwordx4 v[142:145], v194, s[42:43] offset:192
	v_add_u32_e32 v195, 0x10000, v194
	global_load_dwordx4 v[146:149], v195, s[42:43] offset:0
	global_load_dwordx4 v[150:153], v195, s[42:43] offset:64
	global_load_dwordx4 v[154:157], v195, s[42:43] offset:128
	global_load_dwordx4 v[158:161], v195, s[42:43] offset:192
	s_waitcnt vmcnt(0)
	v_pk_fma_f32 v[126:127], v[126:127], v[178:179], v[130:131]
	v_pk_fma_f32 v[128:129], v[128:129], v[180:181], v[132:133]
	v_pk_fma_f32 v[122:123], v[122:123], v[182:183], v[134:135]
	v_pk_fma_f32 v[124:125], v[124:125], v[184:185], v[136:137]
	v_pk_fma_f32 v[118:119], v[118:119], v[186:187], v[138:139]
	v_pk_fma_f32 v[120:121], v[120:121], v[188:189], v[140:141]
	v_pk_fma_f32 v[114:115], v[114:115], v[190:191], v[142:143]
	v_pk_fma_f32 v[116:117], v[116:117], v[192:193], v[144:145]
	global_store_dwordx4 v194, v[126:129], s[46:47] offset:0
	global_store_dwordx4 v194, v[122:125], s[46:47] offset:64
	global_store_dwordx4 v194, v[118:121], s[46:47] offset:128
	global_store_dwordx4 v194, v[114:117], s[46:47] offset:192
	v_pk_fma_f32 v[110:111], v[110:111], v[178:179], v[146:147]
	v_pk_fma_f32 v[112:113], v[112:113], v[180:181], v[148:149]
	v_pk_fma_f32 v[106:107], v[106:107], v[182:183], v[150:151]
	v_pk_fma_f32 v[108:109], v[108:109], v[184:185], v[152:153]
	v_pk_fma_f32 v[102:103], v[102:103], v[186:187], v[154:155]
	v_pk_fma_f32 v[104:105], v[104:105], v[188:189], v[156:157]
	v_pk_fma_f32 v[98:99], v[98:99], v[190:191], v[158:159]
	v_pk_fma_f32 v[100:101], v[100:101], v[192:193], v[160:161]
	global_store_dwordx4 v195, v[110:113], s[46:47] offset:0
	global_store_dwordx4 v195, v[106:109], s[46:47] offset:64
	global_store_dwordx4 v195, v[102:105], s[46:47] offset:128
	global_store_dwordx4 v195, v[98:101], s[46:47] offset:192
	s_waitcnt vmcnt(0)
.Lp3t_none:
	v_readlane_b32 s36, v254, 0
	v_readlane_b32 s37, v254, 1
	v_readlane_b32 s38, v254, 2
	v_readlane_b32 s39, v254, 3
	v_readlane_b32 s40, v254, 4
	v_readlane_b32 s41, v254, 5
	v_readlane_b32 s42, v254, 6
	v_readlane_b32 s43, v254, 7
	v_readlane_b32 s44, v254, 8
	v_readlane_b32 s45, v254, 9
	v_readlane_b32 s46, v254, 10
	v_readlane_b32 s47, v254, 11
	v_readlane_b32 s48, v254, 12
	v_readlane_b32 s49, v254, 13
	v_readlane_b32 s50, v254, 14
	v_readlane_b32 s51, v254, 15
	v_readlane_b32 s4, v254, 55
	v_readlane_b32 s5, v254, 56
	s_mov_b64 s[16:17], s[48:49]
	s_mov_b64 s[18:19], s[50:51]
	s_mov_b64 s[2:3], 0x2000
	s_add_i32 s29, s29, s95
	s_branch .LBB0_1064
